# mLSTM step: q.n partial sums reduced with DPP quad permutes instead of two ds_bpermute round trips; q.n and state-update fragment reads hoisted ahead of their consumers
# baseline (speedup 1.0000x reference)
.LBB0_1693:
	v_ashrrev_i32_e32 v99, 3, v80
	v_lshlrev_b32_e32 v0, 4, v8
	v_and_b32_e32 v84, 0x70, v0
	v_mul_lo_u32 v0, v99, s69
	s_waitcnt lgkmcnt(0)
	s_barrier
	v_lshl_add_u32 v0, v84, 1, v0
	ds_read_b128 v[10:13], v0 offset:54272
	ds_read_b128 v[32:35], v0 offset:54288
	v_lshlrev_b32_e32 v5, 2, v84
	v_or_b32_e32 v6, 0x21400, v5
	ds_read_b128 v[118:121], v6
	ds_read_b128 v[122:125], v6 offset:16
	ds_read_b128 v[200:203], v6 offset:32
	ds_read_b128 v[204:207], v6 offset:48
	v_add_u32_e32 v7, 0x11800, v0
	s_waitcnt lgkmcnt(5)
	v_lshlrev_b32_e32 v0, 16, v10
	v_and_b32_e32 v9, 0xffff0000, v10
	v_or_b32_e32 v10, 0x21410, v5
	v_lshlrev_b32_e32 v14, 16, v11
	v_and_b32_e32 v15, 0xffff0000, v11
	v_lshlrev_b32_e32 v40, 16, v12
	v_and_b32_e32 v41, 0xffff0000, v12
	ds_read_b64 v[82:83], v90
	v_lshlrev_b32_e32 v6, 16, v13
	v_and_b32_e32 v42, 0xffff0000, v13
	s_cmp_gt_u32 s77, 1
	s_waitcnt lgkmcnt(4)
	v_mul_f32_e32 v0, v118, v0
	v_mul_f32_e32 v9, v119, v9
	v_mul_f32_e32 v14, v120, v14
	s_waitcnt lgkmcnt(3)
	v_mul_f32_e32 v36, v122, v40
	v_mul_f32_e32 v13, v125, v42
	v_cvt_pk_bf16_f32 v10, v0, v9
	v_mul_f32_e32 v15, v121, v15
	v_mul_f32_e32 v37, v123, v41
	v_mul_f32_e32 v6, v124, v6
	v_cvt_pk_bf16_f32 v11, v14, v15
	v_cvt_pk_bf16_f32 v12, v36, v37
	v_cvt_pk_bf16_f32 v13, v6, v13
	ds_write_b128 v7, v[10:13]
	v_or_b32_e32 v10, 0x21420, v5
	v_or_b32_e32 v5, 0x21430, v5
	v_lshlrev_b32_e32 v0, 16, v32
	v_and_b32_e32 v6, 0xffff0000, v32
	v_lshlrev_b32_e32 v9, 16, v33
	v_and_b32_e32 v14, 0xffff0000, v33
	v_lshlrev_b32_e32 v15, 16, v34
	v_and_b32_e32 v36, 0xffff0000, v34
	v_lshlrev_b32_e32 v37, 16, v35
	v_and_b32_e32 v38, 0xffff0000, v35
	s_cselect_b64 s[54:55], -1, 0
	s_cmp_lt_u32 s77, 2
	v_ashrrev_i32_e32 v100, 5, v8
	v_and_b32_e32 v101, 31, v8
	s_waitcnt lgkmcnt(3)
	v_mul_f32_e32 v5, v201, v6
	v_mul_f32_e32 v6, v202, v9
	v_mul_f32_e32 v9, v203, v14
	s_waitcnt lgkmcnt(2)
	v_mul_f32_e32 v12, v204, v15
	v_mul_f32_e32 v13, v205, v36
	v_mul_f32_e32 v0, v200, v0
	v_mul_f32_e32 v14, v206, v37
	v_mul_f32_e32 v15, v207, v38
	v_cvt_pk_bf16_f32 v10, v0, v5
	v_cvt_pk_bf16_f32 v11, v6, v9
	v_cvt_pk_bf16_f32 v12, v12, v13
	v_cvt_pk_bf16_f32 v13, v14, v15
	ds_write_b128 v7, v[10:13] offset:16
	s_cbranch_scc1 .LBB0_1723
	v_lshlrev_b32_e32 v178, 2, v3
	v_or_b32_e32 v177, 0x21600, v178
	ds_read_b128 v[208:211], v4
	ds_read_b128 v[212:215], v177
	ds_read_b128 v[216:219], v4 offset:16
	ds_read_b128 v[220:223], v177 offset:16
	ds_read_b128 v[224:227], v177 offset:32
	ds_read_b128 v[228:231], v177 offset:48
	v_lshlrev_b32_e32 v0, 2, v3
	v_or_b32_e32 v3, 0x21600, v0
	s_nop 0
	s_waitcnt lgkmcnt(5)
	v_lshlrev_b32_e32 v9, 16, v208
	v_and_b32_e32 v14, 0xffff0000, v208
	v_add_u32_e32 v10, 0x21610, v0
	v_lshlrev_b32_e32 v15, 16, v209
	v_and_b32_e32 v36, 0xffff0000, v209
	v_lshlrev_b32_e32 v37, 16, v210
	v_and_b32_e32 v38, 0xffff0000, v210
	v_lshlrev_b32_e32 v3, 16, v211
	v_and_b32_e32 v39, 0xffff0000, v211
	s_nop 0
	s_waitcnt lgkmcnt(4)
	v_mul_f32_e32 v14, v213, v14
	v_fmac_f32_e32 v14, v212, v9
	v_fmac_f32_e32 v14, v214, v15
	v_fmac_f32_e32 v14, v215, v36
	s_nop 0
	s_waitcnt lgkmcnt(2)
	v_fmac_f32_e32 v14, v220, v37
	v_fmac_f32_e32 v14, v221, v38
	v_fmac_f32_e32 v14, v222, v3
	v_fmac_f32_e32 v14, v223, v39
	v_add_f32_e32 v3, 0, v14
	v_lshlrev_b32_e32 v9, 16, v216
	v_and_b32_e32 v14, 0xffff0000, v216
	v_add_u32_e32 v4, 0x21620, v0
	v_add_u32_e32 v0, 0x21630, v0
	v_lshlrev_b32_e32 v15, 16, v217
	v_and_b32_e32 v32, 0xffff0000, v217
	v_lshlrev_b32_e32 v33, 16, v218
	v_and_b32_e32 v34, 0xffff0000, v218
	v_lshlrev_b32_e32 v35, 16, v219
	v_and_b32_e32 v36, 0xffff0000, v219
	s_nop 0
	s_waitcnt lgkmcnt(1)
	v_mul_f32_e32 v0, v225, v14
	v_fmac_f32_e32 v0, v224, v9
	v_fmac_f32_e32 v0, v226, v15
	v_fmac_f32_e32 v0, v227, v32
	s_nop 0
	s_waitcnt lgkmcnt(0)
	v_fmac_f32_e32 v0, v228, v33
	v_fmac_f32_e32 v0, v229, v34
	v_fmac_f32_e32 v0, v230, v35
	v_fmac_f32_e32 v0, v231, v36
	v_and_b32_e32 v4, 64, v91
	v_add_f32_e32 v0, v3, v0
	v_xor_b32_e32 v3, 1, v91
	v_add_u32_e32 v9, 64, v4
	v_cmp_lt_i32_e32 vcc, v3, v9
	s_nop 1
	v_cndmask_b32_e32 v3, v91, v3, vcc
	v_lshlrev_b32_e32 v3, 2, v3
	s_nop 1
	v_mov_b32_dpp v3, v0 quad_perm:[1,0,3,2] row_mask:0xf bank_mask:0xf
	s_nop 0
	v_add_f32_e32 v0, v0, v3
	v_xor_b32_e32 v3, 2, v91
	v_cmp_lt_i32_e32 vcc, v3, v9
	s_nop 1
	v_cndmask_b32_e32 v3, v91, v3, vcc
	v_lshlrev_b32_e32 v3, 2, v3
	s_nop 1
	v_mov_b32_dpp v3, v0 quad_perm:[2,3,0,1] row_mask:0xf bank_mask:0xf
	v_cmp_eq_u32_e32 vcc, 0, v85
	s_and_saveexec_b64 s[10:11], vcc
	s_cbranch_execz .LBB0_1696
	s_waitcnt lgkmcnt(0)
	v_add_f32_e32 v0, v0, v3
	v_lshl_add_u32 v2, v2, 2, v92
	ds_write_b32 v2, v0
